# P7 main loop: LDS-DMA issue rebalanced 4/4/4/4 across the four load segments (A(0,0) stage moved L2->L3, A(1,0) stage moved L4->next L1, waits 8/6/8/6), saddr addressing; placement kept
# speedup vs baseline: 1.0085x; 1.0085x over previous
; #define PG8_STAGE(bufoff, gbase, voff) do { _Pragma("unroll") for (int _i = 0; _i < 2; ++_i) \
;         __builtin_amdgcn_global_load_lds((const unsigned*)((const char*)(gbase) + (voff)[_i]), (PG8_LAS unsigned*)(lds + (bufoff) + ldsw + _i * 8192), 16, 0, 0); } while (0)
; #define PG8_LDA(dst, b, h) do { _Pragma("unroll") for (int m = 0; m < 4; ++m) _Pragma("unroll") for (int k = 0; k < 2; ++k) dst[m][k] = *(const PG8_LAS bf16x8*)(lds + PG8_SA(b, h) + aoff + m * 2048 + k * 1024); } while (0)
; #define PG8_LDB(dst, b, h) do { _Pragma("unroll") for (int n = 0; n < 2; ++n) _Pragma("unroll") for (int k = 0; k < 2; ++k) dst[n][k] = *(const PG8_LAS bf16x8*)(lds + PG8_SB(b, h) + boff + n * 2048 + k * 1024); } while (0)
; #define PG8_MMA(ai, bj, At, Bt) do { __builtin_amdgcn_s_setprio(1); _Pragma("unroll") for (int m = 0; m < 4; ++m) _Pragma("unroll") for (int n = 0; n < 2; ++n) _Pragma("unroll") for (int k = 0; k < 2; ++k) \
;         acc[ai][bj][m][n] = __builtin_amdgcn_mfma_f32_16x16x32_bf16(Bt[n][k], At[m][k], acc[ai][bj][m][n], 0, 0, 0); __builtin_amdgcn_s_setprio(0); } while (0)
; #define PG8_WAIT_V(n) asm volatile("s_waitcnt vmcnt(" #n ")" ::: "memory")
; #define PG8_WAIT_L(n) asm volatile("s_waitcnt lgkmcnt(" #n ")" ::: "memory")
; template <class Epi, class Sched, bool ALIGN_EPI = false, bool SP2 = false>
; __device__ __forceinline__ void gemm_phase(PG8_LAS unsigned char* lds, const Gemm g, const Sched& S, const Epi& E) {
;     ...
;             const bool last = (t == nt - 2);
;             const char* a1 = cA + (size_t)(t + 1) * kstep;
;             const char* a2 = last ? nA : cA + (size_t)(t + 2) * kstep; const char* b2 = last ? nB : cB + (size_t)(t + 2) * kstep;
;             const char* a3 = a2 + kstep; const char* b3 = b2 + kstep;
;             if (last && has_next) S.a_ready(nxt);
;             if constexpr (SP2) {
;             PG8_LDB(B0, 0, 0); PG8_LDB(B1, 0, 1); PG8_SCHED; PG8_LDA(At, 0, 0); PG8_STAGE(PG8_SA(1, 1), a1 + hstep, voffA);
;             PG8_WAIT_V(8); PG8_WAIT_L(0); PG8_BAR; PG8_MMA(0, 0, At, B0); PG8_MMA(0, 1, At, B1); PG8_BAR; PG8_SCHED;
;             PG8_LDA(At, 0, 1); PG8_STAGE(PG8_SB(0, 0), b2, voffB); PG8_STAGE(PG8_SB(0, 1), b2 + hstep, voffB); PG8_STAGE(PG8_SA(0, 0), a2, voffA);
;             PG8_WAIT_V(8); PG8_WAIT_L(0); PG8_BAR; PG8_MMA(1, 0, At, B0); PG8_MMA(1, 1, At, B1); PG8_BAR; PG8_SCHED;
.LBB0_1487:
	s_add_u32 s2, s48, 0xfff80080
	s_addc_u32 s3, s49, -1
	s_add_i32 s58, 0, 0x10000
	s_cmp_eq_u32 s57, 28
	s_cselect_b32 s51, s21, s3
	s_cselect_b32 s50, s24, s2
	s_cselect_b32 s23, s19, s56
	s_cselect_b32 s22, s25, s55
	s_add_i32 s59, 0, 0x14000
	v_add_u32_e32 v156, s58, v149
	v_add_u32_e32 v172, s59, v149
	ds_read_b128 v[140:143], v156
	ds_read_b128 v[144:147], v156 offset:1024
	ds_read_b128 v[152:155], v156 offset:2048
	ds_read_b128 v[156:159], v156 offset:3072
	ds_read_b128 v[160:163], v172
	ds_read_b128 v[164:167], v172 offset:1024
	ds_read_b128 v[168:171], v172 offset:2048
	ds_read_b128 v[172:175], v172 offset:3072
	s_add_u32 s100, s48, 0xfff80000
	s_addc_u32 s101, s49, -1
	s_mov_b32 m0, s47
	ds_read_b128 v[176:179], v151
	ds_read_b128 v[180:183], v151 offset:1024
	ds_read_b128 v[200:203], v151 offset:2048
	ds_read_b128 v[204:207], v151 offset:3072
	ds_read_b128 v[208:211], v151 offset:4096
	ds_read_b128 v[212:215], v151 offset:5120
	ds_read_b128 v[216:219], v151 offset:6144
	ds_read_b128 v[232:235], v151 offset:7168
	global_load_lds_dwordx4 v134, s[100:101]
	s_mov_b32 m0, s52
	s_nop 0
	global_load_lds_dwordx4 v132, s[100:101]
	s_add_i32 m0, s35, 0xc000
	s_nop 0
	global_load_lds_dwordx4 v138, s[48:49]
	s_add_i32 m0, s35, 0xe000
	s_nop 0
	global_load_lds_dwordx4 v136, s[48:49]
	s_waitcnt vmcnt(8)
	s_waitcnt lgkmcnt(0)
	s_barrier
	s_setprio 1
	s_waitcnt lgkmcnt(0)
	v_mfma_f32_16x16x32_bf16 v[126:129], v[140:143], v[176:179], v[126:129]
	v_mfma_f32_16x16x32_bf16 v[118:121], v[152:155], v[176:179], v[118:121]
	v_mfma_f32_16x16x32_bf16 v[110:113], v[140:143], v[200:203], v[110:113]
	v_mfma_f32_16x16x32_bf16 v[102:105], v[152:155], v[200:203], v[102:105]
	v_mfma_f32_16x16x32_bf16 v[94:97], v[140:143], v[208:211], v[94:97]
	v_mfma_f32_16x16x32_bf16 v[86:89], v[152:155], v[208:211], v[86:89]
	v_mfma_f32_16x16x32_bf16 v[78:81], v[140:143], v[216:219], v[78:81]
	v_mfma_f32_16x16x32_bf16 v[70:73], v[152:155], v[216:219], v[70:73]
	v_mfma_f32_16x16x32_bf16 v[126:129], v[144:147], v[180:183], v[126:129]
	v_mfma_f32_16x16x32_bf16 v[118:121], v[156:159], v[180:183], v[118:121]
	v_mfma_f32_16x16x32_bf16 v[110:113], v[144:147], v[204:207], v[110:113]
	v_mfma_f32_16x16x32_bf16 v[102:105], v[156:159], v[204:207], v[102:105]
	v_mfma_f32_16x16x32_bf16 v[94:97], v[144:147], v[212:215], v[94:97]
	v_mfma_f32_16x16x32_bf16 v[86:89], v[156:159], v[212:215], v[86:89]
	v_mfma_f32_16x16x32_bf16 v[78:81], v[144:147], v[232:235], v[78:81]
	v_mfma_f32_16x16x32_bf16 v[70:73], v[156:159], v[232:235], v[70:73]
	s_setprio 0
	s_setprio 1
	v_mfma_f32_16x16x32_bf16 v[122:125], v[160:163], v[176:179], v[122:125]
	v_mfma_f32_16x16x32_bf16 v[114:117], v[168:171], v[176:179], v[114:117]
	v_mfma_f32_16x16x32_bf16 v[106:109], v[160:163], v[200:203], v[106:109]
	v_mfma_f32_16x16x32_bf16 v[98:101], v[168:171], v[200:203], v[98:101]
	v_mfma_f32_16x16x32_bf16 v[90:93], v[160:163], v[208:211], v[90:93]
	v_mfma_f32_16x16x32_bf16 v[82:85], v[168:171], v[208:211], v[82:85]
	v_mfma_f32_16x16x32_bf16 v[74:77], v[160:163], v[216:219], v[74:77]
	v_mfma_f32_16x16x32_bf16 v[66:69], v[168:171], v[216:219], v[66:69]
	v_mfma_f32_16x16x32_bf16 v[122:125], v[164:167], v[180:183], v[122:125]
	v_mfma_f32_16x16x32_bf16 v[114:117], v[172:175], v[180:183], v[114:117]
	v_mfma_f32_16x16x32_bf16 v[106:109], v[164:167], v[204:207], v[106:109]
	v_mfma_f32_16x16x32_bf16 v[98:101], v[172:175], v[204:207], v[98:101]
	v_mfma_f32_16x16x32_bf16 v[90:93], v[164:167], v[212:215], v[90:93]
	v_mfma_f32_16x16x32_bf16 v[82:85], v[172:175], v[212:215], v[82:85]
	v_mfma_f32_16x16x32_bf16 v[74:77], v[164:167], v[232:235], v[74:77]
	v_mfma_f32_16x16x32_bf16 v[66:69], v[172:175], v[232:235], v[66:69]
	s_setprio 0
	s_barrier
	s_add_i32 s2, s58, s28
	s_mov_b32 m0, s2
	ds_read_b128 v[176:179], v151 offset:16384
	ds_read_b128 v[180:183], v151 offset:17408
	ds_read_b128 v[200:203], v151 offset:18432
	ds_read_b128 v[204:207], v151 offset:19456
	ds_read_b128 v[208:211], v151 offset:20480
	ds_read_b128 v[212:215], v151 offset:21504
	ds_read_b128 v[216:219], v151 offset:22528
	ds_read_b128 v[232:235], v151 offset:23552
	global_load_lds_dwordx4 v0, s[22:23]
	s_add_i32 m0, s2, 0x2000
	s_add_u32 s2, s22, 0x80000
	s_addc_u32 s3, s23, 0
	s_add_i32 s58, s59, s28
	global_load_lds_dwordx4 v130, s[22:23]
	s_mov_b32 m0, s58
	s_nop 0
	global_load_lds_dwordx4 v0, s[2:3]
	s_add_i32 m0, s58, 0x2000
	s_nop 0
	global_load_lds_dwordx4 v130, s[2:3]
	s_waitcnt vmcnt(6)
	s_waitcnt lgkmcnt(0)
	s_barrier
	s_setprio 1
	s_waitcnt lgkmcnt(0)
	v_mfma_f32_16x16x32_bf16 v[62:65], v[140:143], v[176:179], v[62:65]
	v_mfma_f32_16x16x32_bf16 v[54:57], v[152:155], v[176:179], v[54:57]
	v_mfma_f32_16x16x32_bf16 v[46:49], v[140:143], v[200:203], v[46:49]
	v_mfma_f32_16x16x32_bf16 v[38:41], v[152:155], v[200:203], v[38:41]
	v_mfma_f32_16x16x32_bf16 v[30:33], v[140:143], v[208:211], v[30:33]
	v_mfma_f32_16x16x32_bf16 v[22:25], v[152:155], v[208:211], v[22:25]
	v_mfma_f32_16x16x32_bf16 v[14:17], v[140:143], v[216:219], v[14:17]
	v_mfma_f32_16x16x32_bf16 v[6:9], v[152:155], v[216:219], v[6:9]
	v_mfma_f32_16x16x32_bf16 v[62:65], v[144:147], v[180:183], v[62:65]
	v_mfma_f32_16x16x32_bf16 v[54:57], v[156:159], v[180:183], v[54:57]
	v_mfma_f32_16x16x32_bf16 v[46:49], v[144:147], v[204:207], v[46:49]
	v_mfma_f32_16x16x32_bf16 v[38:41], v[156:159], v[204:207], v[38:41]
	v_mfma_f32_16x16x32_bf16 v[30:33], v[144:147], v[212:215], v[30:33]
	v_mfma_f32_16x16x32_bf16 v[22:25], v[156:159], v[212:215], v[22:25]
	v_mfma_f32_16x16x32_bf16 v[14:17], v[144:147], v[232:235], v[14:17]
	v_mfma_f32_16x16x32_bf16 v[6:9], v[156:159], v[232:235], v[6:9]
	s_setprio 0
	s_setprio 1
	v_mfma_f32_16x16x32_bf16 v[58:61], v[160:163], v[176:179], v[58:61]
	v_mfma_f32_16x16x32_bf16 v[50:53], v[168:171], v[176:179], v[50:53]
	v_mfma_f32_16x16x32_bf16 v[42:45], v[160:163], v[200:203], v[42:45]
	v_mfma_f32_16x16x32_bf16 v[34:37], v[168:171], v[200:203], v[34:37]
	v_mfma_f32_16x16x32_bf16 v[26:29], v[160:163], v[208:211], v[26:29]
	v_mfma_f32_16x16x32_bf16 v[18:21], v[168:171], v[208:211], v[18:21]
	v_mfma_f32_16x16x32_bf16 v[10:13], v[160:163], v[216:219], v[10:13]
	v_mfma_f32_16x16x32_bf16 v[2:5], v[168:171], v[216:219], v[2:5]
	v_mfma_f32_16x16x32_bf16 v[58:61], v[164:167], v[180:183], v[58:61]
	v_mfma_f32_16x16x32_bf16 v[50:53], v[172:175], v[180:183], v[50:53]
	v_mfma_f32_16x16x32_bf16 v[42:45], v[164:167], v[204:207], v[42:45]
	v_mfma_f32_16x16x32_bf16 v[34:37], v[172:175], v[204:207], v[34:37]
	v_mfma_f32_16x16x32_bf16 v[26:29], v[164:167], v[212:215], v[26:29]
	v_mfma_f32_16x16x32_bf16 v[18:21], v[172:175], v[212:215], v[18:21]
	v_mfma_f32_16x16x32_bf16 v[10:13], v[164:167], v[232:235], v[10:13]
	v_mfma_f32_16x16x32_bf16 v[2:5], v[172:175], v[232:235], v[2:5]
	s_setprio 0
	s_barrier
; #define PG8_STAGE(bufoff, gbase, voff) do { _Pragma("unroll") for (int _i = 0; _i < 2; ++_i) \
;         __builtin_amdgcn_global_load_lds((const unsigned*)((const char*)(gbase) + (voff)[_i]), (PG8_LAS unsigned*)(lds + (bufoff) + ldsw + _i * 8192), 16, 0, 0); } while (0)
; #define PG8_LDA(dst, b, h) do { _Pragma("unroll") for (int m = 0; m < 4; ++m) _Pragma("unroll") for (int k = 0; k < 2; ++k) dst[m][k] = *(const PG8_LAS bf16x8*)(lds + PG8_SA(b, h) + aoff + m * 2048 + k * 1024); } while (0)
; #define PG8_LDB(dst, b, h) do { _Pragma("unroll") for (int n = 0; n < 2; ++n) _Pragma("unroll") for (int k = 0; k < 2; ++k) dst[n][k] = *(const PG8_LAS bf16x8*)(lds + PG8_SB(b, h) + boff + n * 2048 + k * 1024); } while (0)
; template <class Epi, class Sched, bool ALIGN_EPI = false, bool SP2 = false>
; __device__ __forceinline__ void gemm_phase(PG8_LAS unsigned char* lds, const Gemm g, const Sched& S, const Epi& E) {
;     ...
;         for (int t = 0; t < nt; t += 2) {
;             const bool last = (t == nt - 2);
;             const char* a1 = cA + (size_t)(t + 1) * kstep;
;             const char* a2 = last ? nA : cA + (size_t)(t + 2) * kstep; const char* b2 = last ? nB : cB + (size_t)(t + 2) * kstep;
;             const char* a3 = a2 + kstep; const char* b3 = b2 + kstep;
;             if (last && has_next) S.a_ready(nxt);
;             if constexpr (SP2) {
;             PG8_LDB(B0, 0, 0); PG8_LDB(B1, 0, 1); PG8_SCHED; PG8_LDA(At, 0, 0); PG8_STAGE(PG8_SA(1, 1), a1 + hstep, voffA);
;             PG8_WAIT_V(8); PG8_WAIT_L(0); PG8_BAR; PG8_MMA(0, 0, At, B0); PG8_MMA(0, 1, At, B1); PG8_BAR; PG8_SCHED;
;             PG8_LDA(At, 0, 1); PG8_STAGE(PG8_SB(0, 0), b2, voffB); PG8_STAGE(PG8_SB(0, 1), b2 + hstep, voffB); PG8_STAGE(PG8_SA(0, 0), a2, voffA);
;             PG8_WAIT_V(8); PG8_WAIT_L(0); PG8_BAR; PG8_MMA(1, 0, At, B0); PG8_MMA(1, 1, At, B1); PG8_BAR; PG8_SCHED;
;             PG8_LDB(B0, 1, 0); PG8_LDB(B1, 1, 1); PG8_SCHED; PG8_LDA(At, 1, 0); PG8_STAGE(PG8_SA(0, 1), a2 + hstep, voffA);
;             PG8_WAIT_V(8); PG8_WAIT_L(0); PG8_BAR; PG8_MMA(0, 0, At, B0); PG8_MMA(0, 1, At, B1); PG8_BAR; PG8_SCHED;
;             PG8_LDA(At, 1, 1); PG8_STAGE(PG8_SB(1, 0), b3, voffB); PG8_STAGE(PG8_SB(1, 1), b3 + hstep, voffB); PG8_STAGE(PG8_SA(1, 0), a3, voffA);
;             PG8_WAIT_V(8); PG8_WAIT_L(0); PG8_BAR; PG8_MMA(1, 0, At, B0); PG8_MMA(1, 1, At, B1); PG8_BAR; PG8_SCHED;
	s_add_i32 s58, 0, 0x18000
	s_add_i32 s59, 0, 0x1c000
	v_add_u32_e32 v156, s58, v149
	v_add_u32_e32 v172, s59, v149
	ds_read_b128 v[140:143], v156
	ds_read_b128 v[144:147], v156 offset:1024
	ds_read_b128 v[152:155], v156 offset:2048
	ds_read_b128 v[156:159], v156 offset:3072
	ds_read_b128 v[160:163], v172
	ds_read_b128 v[164:167], v172 offset:1024
	ds_read_b128 v[168:171], v172 offset:2048
	ds_read_b128 v[172:175], v172 offset:3072
	s_add_u32 s2, s50, 0x80000
	s_addc_u32 s3, s51, 0
	s_mov_b32 m0, s35
	ds_read_b128 v[176:179], v151 offset:32768
	ds_read_b128 v[180:183], v151 offset:33792
	ds_read_b128 v[200:203], v151 offset:34816
	ds_read_b128 v[204:207], v151 offset:35840
	ds_read_b128 v[208:211], v151 offset:36864
	ds_read_b128 v[212:215], v151 offset:37888
	ds_read_b128 v[216:219], v151 offset:38912
	ds_read_b128 v[232:235], v151 offset:39936
	global_load_lds_dwordx4 v134, s[50:51]
	s_mov_b32 m0, s36
	s_nop 0
	global_load_lds_dwordx4 v132, s[50:51]
	s_mov_b32 m0, s37
	s_nop 0
	global_load_lds_dwordx4 v134, s[2:3]
	s_mov_b32 m0, s38
	s_nop 0
	global_load_lds_dwordx4 v132, s[2:3]
	s_waitcnt vmcnt(8)
	s_waitcnt lgkmcnt(0)
	s_barrier
	s_setprio 1
	s_waitcnt lgkmcnt(0)
	v_mfma_f32_16x16x32_bf16 v[126:129], v[140:143], v[176:179], v[126:129]
	v_mfma_f32_16x16x32_bf16 v[118:121], v[152:155], v[176:179], v[118:121]
	v_mfma_f32_16x16x32_bf16 v[110:113], v[140:143], v[200:203], v[110:113]
	v_mfma_f32_16x16x32_bf16 v[102:105], v[152:155], v[200:203], v[102:105]
	v_mfma_f32_16x16x32_bf16 v[94:97], v[140:143], v[208:211], v[94:97]
	v_mfma_f32_16x16x32_bf16 v[86:89], v[152:155], v[208:211], v[86:89]
	v_mfma_f32_16x16x32_bf16 v[78:81], v[140:143], v[216:219], v[78:81]
	v_mfma_f32_16x16x32_bf16 v[70:73], v[152:155], v[216:219], v[70:73]
	v_mfma_f32_16x16x32_bf16 v[126:129], v[144:147], v[180:183], v[126:129]
	v_mfma_f32_16x16x32_bf16 v[118:121], v[156:159], v[180:183], v[118:121]
	v_mfma_f32_16x16x32_bf16 v[110:113], v[144:147], v[204:207], v[110:113]
	v_mfma_f32_16x16x32_bf16 v[102:105], v[156:159], v[204:207], v[102:105]
	v_mfma_f32_16x16x32_bf16 v[94:97], v[144:147], v[212:215], v[94:97]
	v_mfma_f32_16x16x32_bf16 v[86:89], v[156:159], v[212:215], v[86:89]
	v_mfma_f32_16x16x32_bf16 v[78:81], v[144:147], v[232:235], v[78:81]
	v_mfma_f32_16x16x32_bf16 v[70:73], v[156:159], v[232:235], v[70:73]
	s_setprio 0
	s_setprio 1
	v_mfma_f32_16x16x32_bf16 v[122:125], v[160:163], v[176:179], v[122:125]
	v_mfma_f32_16x16x32_bf16 v[114:117], v[168:171], v[176:179], v[114:117]
	v_mfma_f32_16x16x32_bf16 v[106:109], v[160:163], v[200:203], v[106:109]
	v_mfma_f32_16x16x32_bf16 v[98:101], v[168:171], v[200:203], v[98:101]
	v_mfma_f32_16x16x32_bf16 v[90:93], v[160:163], v[208:211], v[90:93]
	v_mfma_f32_16x16x32_bf16 v[82:85], v[168:171], v[208:211], v[82:85]
	v_mfma_f32_16x16x32_bf16 v[74:77], v[160:163], v[216:219], v[74:77]
	v_mfma_f32_16x16x32_bf16 v[66:69], v[168:171], v[216:219], v[66:69]
	v_mfma_f32_16x16x32_bf16 v[122:125], v[164:167], v[180:183], v[122:125]
	v_mfma_f32_16x16x32_bf16 v[114:117], v[172:175], v[180:183], v[114:117]
	v_mfma_f32_16x16x32_bf16 v[106:109], v[164:167], v[204:207], v[106:109]
	v_mfma_f32_16x16x32_bf16 v[98:101], v[172:175], v[204:207], v[98:101]
	v_mfma_f32_16x16x32_bf16 v[90:93], v[164:167], v[212:215], v[90:93]
	v_mfma_f32_16x16x32_bf16 v[82:85], v[172:175], v[212:215], v[82:85]
	v_mfma_f32_16x16x32_bf16 v[74:77], v[164:167], v[232:235], v[74:77]
	v_mfma_f32_16x16x32_bf16 v[66:69], v[172:175], v[232:235], v[66:69]
	s_setprio 0
	s_barrier
	s_add_u32 s100, s22, 0x80
	s_addc_u32 s101, s23, 0
	s_add_i32 s2, s58, s28
	s_mov_b32 m0, s2
	ds_read_b128 v[176:179], v151 offset:49152
	ds_read_b128 v[180:183], v151 offset:50176
	ds_read_b128 v[200:203], v151 offset:51200
	ds_read_b128 v[204:207], v151 offset:52224
	ds_read_b128 v[208:211], v151 offset:53248
	ds_read_b128 v[212:215], v151 offset:54272
	ds_read_b128 v[216:219], v151 offset:55296
	ds_read_b128 v[232:235], v151 offset:56320
	global_load_lds_dwordx4 v0, s[100:101]
	s_add_i32 m0, s2, 0x2000
	s_add_u32 s2, s22, 0x80080
	s_addc_u32 s3, s23, 0
	s_add_i32 s22, s59, s28
	global_load_lds_dwordx4 v130, s[100:101]
	s_mov_b32 m0, s22
	s_nop 0
	global_load_lds_dwordx4 v0, s[2:3]
	s_add_i32 m0, s22, 0x2000
	s_nop 0
	global_load_lds_dwordx4 v130, s[2:3]
	s_waitcnt vmcnt(6)
	s_waitcnt lgkmcnt(0)
	s_barrier
	s_setprio 1
	s_waitcnt lgkmcnt(0)
	v_mfma_f32_16x16x32_bf16 v[62:65], v[140:143], v[176:179], v[62:65]
	v_mfma_f32_16x16x32_bf16 v[54:57], v[152:155], v[176:179], v[54:57]
	v_mfma_f32_16x16x32_bf16 v[46:49], v[140:143], v[200:203], v[46:49]
	v_mfma_f32_16x16x32_bf16 v[38:41], v[152:155], v[200:203], v[38:41]
	v_mfma_f32_16x16x32_bf16 v[30:33], v[140:143], v[208:211], v[30:33]
	v_mfma_f32_16x16x32_bf16 v[22:25], v[152:155], v[208:211], v[22:25]
	v_mfma_f32_16x16x32_bf16 v[14:17], v[140:143], v[216:219], v[14:17]
	v_mfma_f32_16x16x32_bf16 v[6:9], v[152:155], v[216:219], v[6:9]
	v_mfma_f32_16x16x32_bf16 v[62:65], v[144:147], v[180:183], v[62:65]
	v_mfma_f32_16x16x32_bf16 v[54:57], v[156:159], v[180:183], v[54:57]
	v_mfma_f32_16x16x32_bf16 v[46:49], v[144:147], v[204:207], v[46:49]
	v_mfma_f32_16x16x32_bf16 v[38:41], v[156:159], v[204:207], v[38:41]
	v_mfma_f32_16x16x32_bf16 v[30:33], v[144:147], v[212:215], v[30:33]
	v_mfma_f32_16x16x32_bf16 v[22:25], v[156:159], v[212:215], v[22:25]
	v_mfma_f32_16x16x32_bf16 v[14:17], v[144:147], v[232:235], v[14:17]
	v_mfma_f32_16x16x32_bf16 v[6:9], v[156:159], v[232:235], v[6:9]
	s_setprio 0
	s_setprio 1
	v_mfma_f32_16x16x32_bf16 v[58:61], v[160:163], v[176:179], v[58:61]
	v_mfma_f32_16x16x32_bf16 v[50:53], v[168:171], v[176:179], v[50:53]
	v_mfma_f32_16x16x32_bf16 v[42:45], v[160:163], v[200:203], v[42:45]
	v_mfma_f32_16x16x32_bf16 v[34:37], v[168:171], v[200:203], v[34:37]
	v_mfma_f32_16x16x32_bf16 v[26:29], v[160:163], v[208:211], v[26:29]
	v_mfma_f32_16x16x32_bf16 v[18:21], v[168:171], v[208:211], v[18:21]
	v_mfma_f32_16x16x32_bf16 v[10:13], v[160:163], v[216:219], v[10:13]
	v_mfma_f32_16x16x32_bf16 v[2:5], v[168:171], v[216:219], v[2:5]
	v_mfma_f32_16x16x32_bf16 v[58:61], v[164:167], v[180:183], v[58:61]
	v_mfma_f32_16x16x32_bf16 v[50:53], v[172:175], v[180:183], v[50:53]
	v_mfma_f32_16x16x32_bf16 v[42:45], v[164:167], v[204:207], v[42:45]
	v_mfma_f32_16x16x32_bf16 v[34:37], v[172:175], v[204:207], v[34:37]
	v_mfma_f32_16x16x32_bf16 v[26:29], v[164:167], v[212:215], v[26:29]
	v_mfma_f32_16x16x32_bf16 v[18:21], v[172:175], v[212:215], v[18:21]
	v_mfma_f32_16x16x32_bf16 v[10:13], v[164:167], v[232:235], v[10:13]
	v_mfma_f32_16x16x32_bf16 v[2:5], v[172:175], v[232:235], v[2:5]
	s_setprio 0
	s_barrier
	s_add_i32 s57, s57, 2
	s_add_u32 s55, s55, 0x100
	s_addc_u32 s56, s56, 0
	s_add_u32 s48, s48, 0x100
	s_addc_u32 s49, s49, 0
	s_cmp_gt_u32 s57, 29
	s_cbranch_scc0 .LBB0_1487
	s_and_b64 vcc, exec, s[16:17]
	s_cbranch_vccz .LBB0_1490
	s_barrier
; __device__ __forceinline__ unsigned pk2(float lo, float hi) { unsigned r; asm volatile("v_cvt_pk_bf16_f32 %0, %1, %2" : "=v"(r) : "v"(lo), "v"(hi)); return r; }
;     __device__ __forceinline__ void operator()(const f32x4 (&acc)[2][2][4][2], const Unit& u, int wr, int wc, int fr, int fq) const {
;         const int row0 = u.pm * BM + wr * 64 + fr, col0 = u.pn * HALF + wc * 32 + 8 * fq;
;         float rs[2][4];
; #pragma unroll
;         for (int ai = 0; ai < 2; ++ai)
; #pragma unroll
;             for (int m = 0; m < 4; ++m) rs[ai][m] = ssq[row0 + ai * HALF + m * 16];
; #pragma unroll
;         for (int ai = 0; ai < 2; ++ai)
; #pragma unroll
;             for (int m = 0; m < 4; ++m) { bf16_t* rowp = O + (size_t)(row0 + ai * HALF + m * 16) * DFF + col0; const float rsv = rsqrtf(rs[ai][m] * (1.f / D) + EPS);
;                 const float rs2 = rsv * rsv, nrs = -1.4426950409f * rsv;
;                 float v[8];
; #pragma unroll
;                 for (int n = 0; n < 2; ++n)
; #pragma unroll
;                     for (int j = 0; j < 4; ++j) {
;                         const float g0 = acc[ai][0][m][n][j], u0 = acc[ai][1][m][n][j];
;                         v[n * 4 + j] = (g0 * u0) * (rs2 * __builtin_amdgcn_rcpf(1.0f + __builtin_amdgcn_exp2f(g0 * nrs))); }
;                 u32x4 w; w.x = pk2(v[0], v[1]); w.y = pk2(v[2], v[3]); w.z = pk2(v[4], v[5]); w.w = pk2(v[6], v[7]);
;                 *(u32x4*)rowp = w; }
.LBB0_1490:
	v_lshl_add_u32 v144, s46, 8, v148
	v_ashrrev_i32_e32 v145, 31, v144
	v_lshl_add_u64 v[140:141], v[144:145], 2, s[12:13]
	flat_load_dword v146, v[140:141]
	flat_load_dword v164, v[140:141] offset:64
	flat_load_dword v162, v[140:141] offset:128
	flat_load_dword v160, v[140:141] offset:192
	flat_load_dword v158, v[140:141] offset:512
	flat_load_dword v156, v[140:141] offset:576
	flat_load_dword v154, v[140:141] offset:640
	flat_load_dword v152, v[140:141] offset:704
	v_mov_b32_e32 v166, v126
	v_lshl_or_b32 v142, s54, 7, v150
	v_ashrrev_i32_e32 v143, 31, v142
	v_mov_b64_e32 v[140:141], s[8:9]
	v_or_b32_e32 v165, 16, v144
	v_or_b32_e32 v163, 32, v144
	v_or_b32_e32 v161, 48, v144
	v_add_u32_e32 v159, 0x80, v144
	v_add_u32_e32 v157, 0x90, v144
	v_add_u32_e32 v155, 0xa0, v144
	v_add_u32_e32 v153, 0xb0, v144
	v_mad_i64_i32 v[144:145], s[2:3], v144, s34, v[140:141]
	s_mov_b64 s[22:23], -1
	s_mov_b64 s[56:57], s[94:95]
	s_waitcnt vmcnt(0) lgkmcnt(0)
	v_fmamk_f32 v146, v146, 0x3a000000, v223
	v_cmp_gt_f32_e32 vcc, s29, v146
	v_mul_f32_e32 v147, 0x4b800000, v146
	s_nop 0
	v_cndmask_b32_e32 v146, v146, v147, vcc
	v_rsq_f32_e32 v146, v146
	s_nop 0
	v_mul_f32_e32 v147, 0x45800000, v146
	v_cndmask_b32_e32 v146, v146, v147, vcc
	v_mul_f32_e32 v168, 0xbfb8aa3b, v146
	v_mul_f32_e32 v147, v146, v146
	v_mul_f32_e32 v146, v126, v168
	v_exp_f32_e32 v146, v146
	s_nop 0
	v_add_f32_e32 v146, 1.0, v146
	v_rcp_f32_e32 v167, v146
	v_mov_b32_e32 v146, v122
	v_mul_f32_e32 v122, v127, v168
	v_exp_f32_e32 v122, v122
	v_pk_mul_f32 v[166:167], v[146:147], v[166:167]
	v_mov_b32_e32 v146, v123
	v_mul_f32_e32 v126, v166, v167
	v_add_f32_e32 v122, 1.0, v122
	v_rcp_f32_e32 v167, v122
	v_mov_b32_e32 v166, v127
	v_pk_mul_f32 v[122:123], v[146:147], v[166:167]
	s_nop 0
	v_mul_f32_e32 v127, v122, v123
	v_mul_f32_e32 v122, v128, v168
	v_exp_f32_e32 v122, v122
	v_mov_b32_e32 v146, v124
	v_add_f32_e32 v122, 1.0, v122
	v_rcp_f32_e32 v123, v122
	v_mov_b32_e32 v122, v128
	v_pk_mul_f32 v[122:123], v[146:147], v[122:123]
	s_nop 0
	v_mul_f32_e32 v124, v122, v123
	v_mul_f32_e32 v122, v129, v168
	v_exp_f32_e32 v122, v122
	v_mov_b32_e32 v146, v125
	v_add_f32_e32 v122, 1.0, v122
	v_rcp_f32_e32 v123, v122
	v_mov_b32_e32 v122, v129
	v_pk_mul_f32 v[122:123], v[146:147], v[122:123]
	s_nop 0
	v_mul_f32_e32 v125, v122, v123
	v_mul_f32_e32 v122, v118, v168
	v_exp_f32_e32 v122, v122
	v_mov_b32_e32 v146, v114
	v_mul_f32_e32 v114, v119, v168
	v_exp_f32_e32 v114, v114
	v_add_f32_e32 v122, 1.0, v122
	v_rcp_f32_e32 v123, v122
	v_mov_b32_e32 v122, v118
	v_add_f32_e32 v114, 1.0, v114
	v_pk_mul_f32 v[122:123], v[146:147], v[122:123]
	s_nop 0
	v_mul_f32_e32 v118, v122, v123
	v_rcp_f32_e32 v123, v114
	v_mov_b32_e32 v146, v115
	v_mov_b32_e32 v122, v119
	v_pk_mul_f32 v[114:115], v[146:147], v[122:123]
	s_nop 0
	v_mul_f32_e32 v119, v114, v115
	v_mul_f32_e32 v114, v120, v168
	v_exp_f32_e32 v114, v114
	v_mov_b32_e32 v146, v116
	v_cvt_pk_bf16_f32 v116, v126, v127
	v_add_f32_e32 v114, 1.0, v114
	v_rcp_f32_e32 v115, v114
	v_mov_b32_e32 v114, v120
	v_pk_mul_f32 v[114:115], v[146:147], v[114:115]
	s_nop 0
	v_mul_f32_e32 v122, v114, v115
	v_mul_f32_e32 v114, v121, v168
	v_exp_f32_e32 v114, v114
	v_mov_b32_e32 v146, v117
	v_cvt_pk_bf16_f32 v117, v124, v125
	v_cvt_pk_bf16_f32 v118, v118, v119
	v_add_f32_e32 v114, 1.0, v114
	v_rcp_f32_e32 v115, v114
	v_mov_b32_e32 v114, v121
	v_pk_mul_f32 v[114:115], v[146:147], v[114:115]
	s_nop 0
	v_mul_f32_e32 v123, v114, v115
	v_lshlrev_b64 v[114:115], 1, v[142:143]
	v_lshl_add_u64 v[120:121], v[144:145], 0, v[114:115]
	v_cvt_pk_bf16_f32 v119, v122, v123
	flat_store_dwordx4 v[120:121], v[116:119]
	v_mov_b32_e32 v120, v110
	s_nop 0
	v_fmamk_f32 v118, v164, 0x3a000000, v223
	v_cmp_gt_f32_e32 vcc, s29, v118
	v_mul_f32_e32 v119, 0x4b800000, v118
	v_mad_i64_i32 v[116:117], s[2:3], v165, s34, v[140:141]
	v_cndmask_b32_e32 v118, v118, v119, vcc
	v_rsq_f32_e32 v118, v118
	s_nop 0
	v_mul_f32_e32 v119, 0x45800000, v118
	v_cndmask_b32_e32 v118, v118, v119, vcc
	v_mul_f32_e32 v122, 0xbfb8aa3b, v118
	v_mul_f32_e32 v119, v118, v118
	v_mul_f32_e32 v118, v110, v122
	v_exp_f32_e32 v118, v118
	s_nop 0
	v_add_f32_e32 v118, 1.0, v118
	v_rcp_f32_e32 v121, v118
	v_mov_b32_e32 v118, v106
	v_mul_f32_e32 v106, v111, v122
	v_exp_f32_e32 v106, v106
	v_pk_mul_f32 v[120:121], v[118:119], v[120:121]
	v_mov_b32_e32 v118, v107
	v_mul_f32_e32 v110, v120, v121
	v_add_f32_e32 v106, 1.0, v106
	v_rcp_f32_e32 v121, v106
	v_mov_b32_e32 v120, v111
	v_pk_mul_f32 v[106:107], v[118:119], v[120:121]
	s_nop 0
	v_mul_f32_e32 v111, v106, v107
	v_mul_f32_e32 v106, v112, v122
	v_exp_f32_e32 v106, v106
	v_mov_b32_e32 v118, v108
	v_add_f32_e32 v106, 1.0, v106
	v_rcp_f32_e32 v107, v106
	v_mov_b32_e32 v106, v112
	v_pk_mul_f32 v[106:107], v[118:119], v[106:107]
	s_nop 0
	v_mul_f32_e32 v108, v106, v107
	v_mul_f32_e32 v106, v113, v122
	v_exp_f32_e32 v106, v106
	v_mov_b32_e32 v118, v109
	v_add_f32_e32 v106, 1.0, v106
	v_rcp_f32_e32 v107, v106
	v_mov_b32_e32 v106, v113
	v_pk_mul_f32 v[106:107], v[118:119], v[106:107]
	s_nop 0
	v_mul_f32_e32 v109, v106, v107
	v_mul_f32_e32 v106, v102, v122
	v_exp_f32_e32 v106, v106
	v_mov_b32_e32 v118, v98
	v_mul_f32_e32 v98, v103, v122
	v_exp_f32_e32 v98, v98
	v_add_f32_e32 v106, 1.0, v106
	v_rcp_f32_e32 v107, v106
	v_mov_b32_e32 v106, v102
	v_add_f32_e32 v98, 1.0, v98
	v_pk_mul_f32 v[106:107], v[118:119], v[106:107]
	s_nop 0
	v_mul_f32_e32 v112, v106, v107
	v_rcp_f32_e32 v107, v98
	v_mov_b32_e32 v118, v99
	v_mov_b32_e32 v106, v103
	v_lshl_add_u64 v[102:103], v[116:117], 0, v[114:115]
	v_pk_mul_f32 v[98:99], v[118:119], v[106:107]
	v_mov_b32_e32 v118, v100
	v_mul_f32_e32 v106, v98, v99
; __device__ __forceinline__ unsigned pk2(float lo, float hi) { unsigned r; asm volatile("v_cvt_pk_bf16_f32 %0, %1, %2" : "=v"(r) : "v"(lo), "v"(hi)); return r; }
;     __device__ __forceinline__ void operator()(const f32x4 (&acc)[2][2][4][2], const Unit& u, int wr, int wc, int fr, int fq) const {
;     ...
;         for (int ai = 0; ai < 2; ++ai)
; #pragma unroll
;             for (int m = 0; m < 4; ++m) { bf16_t* rowp = O + (size_t)(row0 + ai * HALF + m * 16) * DFF + col0; const float rsv = rsqrtf(rs[ai][m] * (1.f / D) + EPS);
;                 const float rs2 = rsv * rsv, nrs = -1.4426950409f * rsv;
;                 float v[8];
; #pragma unroll
;                 for (int n = 0; n < 2; ++n)
; #pragma unroll
;                     for (int j = 0; j < 4; ++j) {
;                         const float g0 = acc[ai][0][m][n][j], u0 = acc[ai][1][m][n][j];
;                         v[n * 4 + j] = (g0 * u0) * (rs2 * __builtin_amdgcn_rcpf(1.0f + __builtin_amdgcn_exp2f(g0 * nrs))); }
;                 u32x4 w; w.x = pk2(v[0], v[1]); w.y = pk2(v[2], v[3]); w.z = pk2(v[4], v[5]); w.w = pk2(v[6], v[7]);
;                 *(u32x4*)rowp = w; }
	v_mul_f32_e32 v98, v104, v122
	v_exp_f32_e32 v98, v98
	s_nop 0
	v_add_f32_e32 v98, 1.0, v98
	v_rcp_f32_e32 v99, v98
	v_mov_b32_e32 v98, v104
	v_pk_mul_f32 v[98:99], v[118:119], v[98:99]
	s_nop 0
	v_mul_f32_e32 v104, v98, v99
	v_mul_f32_e32 v98, v105, v122
	v_exp_f32_e32 v98, v98
	v_mov_b32_e32 v118, v101
	v_add_f32_e32 v98, 1.0, v98
	v_rcp_f32_e32 v99, v98
	v_mov_b32_e32 v98, v105
	v_pk_mul_f32 v[98:99], v[118:119], v[98:99]
	s_nop 0
	v_mul_f32_e32 v101, v98, v99
	v_cvt_pk_bf16_f32 v98, v110, v111
	v_cvt_pk_bf16_f32 v99, v108, v109
	v_cvt_pk_bf16_f32 v100, v112, v106
	v_cvt_pk_bf16_f32 v101, v104, v101
	flat_store_dwordx4 v[102:103], v[98:101]
	v_mov_b32_e32 v102, v94
	s_nop 0
	v_fmamk_f32 v100, v162, 0x3a000000, v223
	v_cmp_gt_f32_e32 vcc, s29, v100
	v_mul_f32_e32 v101, 0x4b800000, v100
	v_mad_i64_i32 v[98:99], s[2:3], v163, s34, v[140:141]
	v_cndmask_b32_e32 v100, v100, v101, vcc
	v_rsq_f32_e32 v100, v100
	s_nop 0
	v_mul_f32_e32 v101, 0x45800000, v100
	v_cndmask_b32_e32 v100, v100, v101, vcc
	v_mul_f32_e32 v104, 0xbfb8aa3b, v100
	v_mul_f32_e32 v101, v100, v100
	v_mul_f32_e32 v100, v94, v104
	v_exp_f32_e32 v100, v100
	s_nop 0
	v_add_f32_e32 v100, 1.0, v100
	v_rcp_f32_e32 v103, v100
	v_mov_b32_e32 v100, v90
	v_mul_f32_e32 v90, v95, v104
	v_exp_f32_e32 v90, v90
	v_pk_mul_f32 v[102:103], v[100:101], v[102:103]
	v_mov_b32_e32 v100, v91
	v_mul_f32_e32 v94, v102, v103
	v_add_f32_e32 v90, 1.0, v90
	v_rcp_f32_e32 v103, v90
	v_mov_b32_e32 v102, v95
	v_pk_mul_f32 v[90:91], v[100:101], v[102:103]
	s_nop 0
	v_mul_f32_e32 v95, v90, v91
	v_mul_f32_e32 v90, v96, v104
	v_exp_f32_e32 v90, v90
	v_mov_b32_e32 v100, v92
	v_add_f32_e32 v90, 1.0, v90
	v_rcp_f32_e32 v91, v90
	v_mov_b32_e32 v90, v96
	v_pk_mul_f32 v[90:91], v[100:101], v[90:91]
	s_nop 0
	v_mul_f32_e32 v92, v90, v91
	v_mul_f32_e32 v90, v97, v104
	v_exp_f32_e32 v90, v90
	v_mov_b32_e32 v100, v93
	v_add_f32_e32 v90, 1.0, v90
	v_rcp_f32_e32 v91, v90
	v_mov_b32_e32 v90, v97
	v_pk_mul_f32 v[90:91], v[100:101], v[90:91]
	s_nop 0
	v_mul_f32_e32 v93, v90, v91
	v_mul_f32_e32 v90, v86, v104
	v_exp_f32_e32 v90, v90
	v_mov_b32_e32 v100, v82
	v_mul_f32_e32 v82, v87, v104
	v_exp_f32_e32 v82, v82
	v_add_f32_e32 v90, 1.0, v90
	v_rcp_f32_e32 v91, v90
	v_mov_b32_e32 v90, v86
	v_add_f32_e32 v82, 1.0, v82
	v_pk_mul_f32 v[90:91], v[100:101], v[90:91]
	s_nop 0
	v_mul_f32_e32 v96, v90, v91
	v_rcp_f32_e32 v91, v82
	v_mov_b32_e32 v100, v83
	v_mov_b32_e32 v90, v87
	v_lshl_add_u64 v[86:87], v[98:99], 0, v[114:115]
	v_pk_mul_f32 v[82:83], v[100:101], v[90:91]
	v_mov_b32_e32 v100, v84
	v_mul_f32_e32 v90, v82, v83
	v_mul_f32_e32 v82, v88, v104
	v_exp_f32_e32 v82, v82
	s_nop 0
	v_add_f32_e32 v82, 1.0, v82
	v_rcp_f32_e32 v83, v82
	v_mov_b32_e32 v82, v88
	v_pk_mul_f32 v[82:83], v[100:101], v[82:83]
	s_nop 0
	v_mul_f32_e32 v88, v82, v83
	v_mul_f32_e32 v82, v89, v104
	v_exp_f32_e32 v82, v82
	v_mov_b32_e32 v100, v85
	v_add_f32_e32 v82, 1.0, v82
	v_rcp_f32_e32 v83, v82
	v_mov_b32_e32 v82, v89
	v_pk_mul_f32 v[82:83], v[100:101], v[82:83]
	s_nop 0
	v_mul_f32_e32 v85, v82, v83
	v_cvt_pk_bf16_f32 v82, v94, v95
	v_cvt_pk_bf16_f32 v83, v92, v93
	v_cvt_pk_bf16_f32 v84, v96, v90
	v_cvt_pk_bf16_f32 v85, v88, v85
	flat_store_dwordx4 v[86:87], v[82:85]
	v_mov_b32_e32 v86, v78
	s_nop 0
	v_fmamk_f32 v84, v160, 0x3a000000, v223
	v_cmp_gt_f32_e32 vcc, s29, v84
	v_mul_f32_e32 v85, 0x4b800000, v84
	v_mad_i64_i32 v[82:83], s[2:3], v161, s34, v[140:141]
	v_cndmask_b32_e32 v84, v84, v85, vcc
	v_rsq_f32_e32 v84, v84
	s_nop 0
	v_mul_f32_e32 v85, 0x45800000, v84
	v_cndmask_b32_e32 v84, v84, v85, vcc
	v_mul_f32_e32 v88, 0xbfb8aa3b, v84
	v_mul_f32_e32 v85, v84, v84
	v_mul_f32_e32 v84, v78, v88
	v_exp_f32_e32 v84, v84
	s_nop 0
	v_add_f32_e32 v84, 1.0, v84
	v_rcp_f32_e32 v87, v84
	v_mov_b32_e32 v84, v74
	v_mul_f32_e32 v74, v79, v88
	v_exp_f32_e32 v74, v74
	v_pk_mul_f32 v[86:87], v[84:85], v[86:87]
	v_mov_b32_e32 v84, v75
	v_mul_f32_e32 v78, v86, v87
	v_add_f32_e32 v74, 1.0, v74
	v_rcp_f32_e32 v87, v74
	v_mov_b32_e32 v86, v79
	v_pk_mul_f32 v[74:75], v[84:85], v[86:87]
	s_nop 0
	v_mul_f32_e32 v79, v74, v75
	v_mul_f32_e32 v74, v80, v88
	v_exp_f32_e32 v74, v74
	v_mov_b32_e32 v84, v76
	v_add_f32_e32 v74, 1.0, v74
	v_rcp_f32_e32 v75, v74
	v_mov_b32_e32 v74, v80
	v_pk_mul_f32 v[74:75], v[84:85], v[74:75]
	s_nop 0
	v_mul_f32_e32 v76, v74, v75
	v_mul_f32_e32 v74, v81, v88
	v_exp_f32_e32 v74, v74
	v_mov_b32_e32 v84, v77
	v_add_f32_e32 v74, 1.0, v74
	v_rcp_f32_e32 v75, v74
	v_mov_b32_e32 v74, v81
	v_pk_mul_f32 v[74:75], v[84:85], v[74:75]
	s_nop 0
	v_mul_f32_e32 v77, v74, v75
	v_mul_f32_e32 v74, v70, v88
	v_exp_f32_e32 v74, v74
	v_mov_b32_e32 v84, v66
	v_mul_f32_e32 v66, v71, v88
	v_exp_f32_e32 v66, v66
	v_add_f32_e32 v74, 1.0, v74
	v_rcp_f32_e32 v75, v74
	v_mov_b32_e32 v74, v70
	v_add_f32_e32 v66, 1.0, v66
	v_pk_mul_f32 v[74:75], v[84:85], v[74:75]
	s_nop 0
	v_mul_f32_e32 v80, v74, v75
	v_rcp_f32_e32 v75, v66
	v_mov_b32_e32 v84, v67
	v_mov_b32_e32 v74, v71
	v_lshl_add_u64 v[70:71], v[82:83], 0, v[114:115]
	v_pk_mul_f32 v[66:67], v[84:85], v[74:75]
	v_mov_b32_e32 v84, v68
	v_mul_f32_e32 v74, v66, v67
	v_mul_f32_e32 v66, v72, v88
	v_exp_f32_e32 v66, v66
	s_nop 0
	v_add_f32_e32 v66, 1.0, v66
	v_rcp_f32_e32 v67, v66
	v_mov_b32_e32 v66, v72
	v_pk_mul_f32 v[66:67], v[84:85], v[66:67]
	s_nop 0
	v_mul_f32_e32 v72, v66, v67
	v_mul_f32_e32 v66, v73, v88
	v_exp_f32_e32 v66, v66
	v_mov_b32_e32 v84, v69
	v_add_f32_e32 v66, 1.0, v66
	v_rcp_f32_e32 v67, v66
	v_mov_b32_e32 v66, v73
	v_pk_mul_f32 v[66:67], v[84:85], v[66:67]
	s_nop 0
	v_mul_f32_e32 v69, v66, v67
	v_cvt_pk_bf16_f32 v66, v78, v79
	v_cvt_pk_bf16_f32 v67, v76, v77
	v_cvt_pk_bf16_f32 v68, v80, v74
	v_cvt_pk_bf16_f32 v69, v72, v69
; __device__ __forceinline__ unsigned pk2(float lo, float hi) { unsigned r; asm volatile("v_cvt_pk_bf16_f32 %0, %1, %2" : "=v"(r) : "v"(lo), "v"(hi)); return r; }
;     __device__ __forceinline__ void operator()(const f32x4 (&acc)[2][2][4][2], const Unit& u, int wr, int wc, int fr, int fq) const {
;     ...
;         for (int ai = 0; ai < 2; ++ai)
; #pragma unroll
;             for (int m = 0; m < 4; ++m) { bf16_t* rowp = O + (size_t)(row0 + ai * HALF + m * 16) * DFF + col0; const float rsv = rsqrtf(rs[ai][m] * (1.f / D) + EPS);
;                 const float rs2 = rsv * rsv, nrs = -1.4426950409f * rsv;
;                 float v[8];
; #pragma unroll
;                 for (int n = 0; n < 2; ++n)
; #pragma unroll
;                     for (int j = 0; j < 4; ++j) {
;                         const float g0 = acc[ai][0][m][n][j], u0 = acc[ai][1][m][n][j];
;                         v[n * 4 + j] = (g0 * u0) * (rs2 * __builtin_amdgcn_rcpf(1.0f + __builtin_amdgcn_exp2f(g0 * nrs))); }
;                 u32x4 w; w.x = pk2(v[0], v[1]); w.y = pk2(v[2], v[3]); w.z = pk2(v[4], v[5]); w.w = pk2(v[6], v[7]);
;                 *(u32x4*)rowp = w; }
	flat_store_dwordx4 v[70:71], v[66:69]
	v_mov_b32_e32 v70, v62
	s_nop 0
	v_fmamk_f32 v68, v158, 0x3a000000, v223
	v_cmp_gt_f32_e32 vcc, s29, v68
	v_mul_f32_e32 v69, 0x4b800000, v68
	v_mad_i64_i32 v[66:67], s[2:3], v159, s34, v[140:141]
	v_cndmask_b32_e32 v68, v68, v69, vcc
	v_rsq_f32_e32 v68, v68
	s_nop 0
	v_mul_f32_e32 v69, 0x45800000, v68
	v_cndmask_b32_e32 v68, v68, v69, vcc
	v_mul_f32_e32 v72, 0xbfb8aa3b, v68
	v_mul_f32_e32 v69, v68, v68
	v_mul_f32_e32 v68, v62, v72
	v_exp_f32_e32 v68, v68
	s_nop 0
	v_add_f32_e32 v68, 1.0, v68
	v_rcp_f32_e32 v71, v68
	v_mov_b32_e32 v68, v58
	v_mul_f32_e32 v58, v63, v72
	v_exp_f32_e32 v58, v58
	v_pk_mul_f32 v[70:71], v[68:69], v[70:71]
	v_mov_b32_e32 v68, v59
	v_mul_f32_e32 v62, v70, v71
	v_add_f32_e32 v58, 1.0, v58
	v_rcp_f32_e32 v71, v58
	v_mov_b32_e32 v70, v63
	v_pk_mul_f32 v[58:59], v[68:69], v[70:71]
	s_nop 0
	v_mul_f32_e32 v63, v58, v59
	v_mul_f32_e32 v58, v64, v72
	v_exp_f32_e32 v58, v58
	v_mov_b32_e32 v68, v60
	v_add_f32_e32 v58, 1.0, v58
	v_rcp_f32_e32 v59, v58
	v_mov_b32_e32 v58, v64
	v_pk_mul_f32 v[58:59], v[68:69], v[58:59]
	s_nop 0
	v_mul_f32_e32 v60, v58, v59
	v_mul_f32_e32 v58, v65, v72
	v_exp_f32_e32 v58, v58
	v_mov_b32_e32 v68, v61
	v_add_f32_e32 v58, 1.0, v58
	v_rcp_f32_e32 v59, v58
	v_mov_b32_e32 v58, v65
	v_pk_mul_f32 v[58:59], v[68:69], v[58:59]
	s_nop 0
	v_mul_f32_e32 v61, v58, v59
	v_mul_f32_e32 v58, v54, v72
	v_exp_f32_e32 v58, v58
	v_mov_b32_e32 v68, v50
	v_mul_f32_e32 v50, v55, v72
	v_exp_f32_e32 v50, v50
	v_add_f32_e32 v58, 1.0, v58
	v_rcp_f32_e32 v59, v58
	v_mov_b32_e32 v58, v54
	v_add_f32_e32 v50, 1.0, v50
	v_pk_mul_f32 v[58:59], v[68:69], v[58:59]
	s_nop 0
	v_mul_f32_e32 v64, v58, v59
	v_rcp_f32_e32 v59, v50
	v_mov_b32_e32 v68, v51
	v_mov_b32_e32 v58, v55
	v_lshl_add_u64 v[54:55], v[66:67], 0, v[114:115]
	v_pk_mul_f32 v[50:51], v[68:69], v[58:59]
	v_mov_b32_e32 v68, v52
	v_mul_f32_e32 v58, v50, v51
	v_mul_f32_e32 v50, v56, v72
	v_exp_f32_e32 v50, v50
	s_nop 0
	v_add_f32_e32 v50, 1.0, v50
	v_rcp_f32_e32 v51, v50
	v_mov_b32_e32 v50, v56
	v_pk_mul_f32 v[50:51], v[68:69], v[50:51]
	s_nop 0
	v_mul_f32_e32 v56, v50, v51
	v_mul_f32_e32 v50, v57, v72
	v_exp_f32_e32 v50, v50
	v_mov_b32_e32 v68, v53
	v_add_f32_e32 v50, 1.0, v50
	v_rcp_f32_e32 v51, v50
	v_mov_b32_e32 v50, v57
	v_pk_mul_f32 v[50:51], v[68:69], v[50:51]
	s_nop 0
	v_mul_f32_e32 v53, v50, v51
	v_cvt_pk_bf16_f32 v50, v62, v63
	v_cvt_pk_bf16_f32 v51, v60, v61
	v_cvt_pk_bf16_f32 v52, v64, v58
	v_cvt_pk_bf16_f32 v53, v56, v53
	flat_store_dwordx4 v[54:55], v[50:53]
	v_mov_b32_e32 v54, v46
	s_nop 0
	v_fmamk_f32 v52, v156, 0x3a000000, v223
	v_cmp_gt_f32_e32 vcc, s29, v52
	v_mul_f32_e32 v53, 0x4b800000, v52
	v_mad_i64_i32 v[50:51], s[2:3], v157, s34, v[140:141]
	v_cndmask_b32_e32 v52, v52, v53, vcc
	v_rsq_f32_e32 v52, v52
	s_nop 0
	v_mul_f32_e32 v53, 0x45800000, v52
	v_cndmask_b32_e32 v52, v52, v53, vcc
	v_mul_f32_e32 v56, 0xbfb8aa3b, v52
	v_mul_f32_e32 v53, v52, v52
	v_mul_f32_e32 v52, v46, v56
	v_exp_f32_e32 v52, v52
	s_nop 0
	v_add_f32_e32 v52, 1.0, v52
	v_rcp_f32_e32 v55, v52
	v_mov_b32_e32 v52, v42
	v_mul_f32_e32 v42, v47, v56
	v_exp_f32_e32 v42, v42
	v_pk_mul_f32 v[54:55], v[52:53], v[54:55]
	v_mov_b32_e32 v52, v43
	v_mul_f32_e32 v46, v54, v55
	v_add_f32_e32 v42, 1.0, v42
	v_rcp_f32_e32 v55, v42
	v_mov_b32_e32 v54, v47
	v_pk_mul_f32 v[42:43], v[52:53], v[54:55]
	s_nop 0
	v_mul_f32_e32 v47, v42, v43
	v_mul_f32_e32 v42, v48, v56
	v_exp_f32_e32 v42, v42
	v_mov_b32_e32 v52, v44
	v_add_f32_e32 v42, 1.0, v42
	v_rcp_f32_e32 v43, v42
	v_mov_b32_e32 v42, v48
	v_pk_mul_f32 v[42:43], v[52:53], v[42:43]
	s_nop 0
	v_mul_f32_e32 v44, v42, v43
	v_mul_f32_e32 v42, v49, v56
	v_exp_f32_e32 v42, v42
	v_mov_b32_e32 v52, v45
	v_add_f32_e32 v42, 1.0, v42
	v_rcp_f32_e32 v43, v42
	v_mov_b32_e32 v42, v49
	v_pk_mul_f32 v[42:43], v[52:53], v[42:43]
	s_nop 0
	v_mul_f32_e32 v45, v42, v43
	v_mul_f32_e32 v42, v38, v56
	v_exp_f32_e32 v42, v42
	v_mov_b32_e32 v52, v34
	v_mul_f32_e32 v34, v39, v56
	v_exp_f32_e32 v34, v34
	v_add_f32_e32 v42, 1.0, v42
	v_rcp_f32_e32 v43, v42
	v_mov_b32_e32 v42, v38
	v_add_f32_e32 v34, 1.0, v34
	v_pk_mul_f32 v[42:43], v[52:53], v[42:43]
	s_nop 0
	v_mul_f32_e32 v48, v42, v43
	v_rcp_f32_e32 v43, v34
	v_mov_b32_e32 v52, v35
	v_mov_b32_e32 v42, v39
	v_lshl_add_u64 v[38:39], v[50:51], 0, v[114:115]
	v_pk_mul_f32 v[34:35], v[52:53], v[42:43]
	v_mov_b32_e32 v52, v36
	v_mul_f32_e32 v42, v34, v35
	v_mul_f32_e32 v34, v40, v56
	v_exp_f32_e32 v34, v34
	s_nop 0
	v_add_f32_e32 v34, 1.0, v34
	v_rcp_f32_e32 v35, v34
	v_mov_b32_e32 v34, v40
	v_pk_mul_f32 v[34:35], v[52:53], v[34:35]
	s_nop 0
	v_mul_f32_e32 v40, v34, v35
	v_mul_f32_e32 v34, v41, v56
	v_exp_f32_e32 v34, v34
	v_mov_b32_e32 v52, v37
	v_add_f32_e32 v34, 1.0, v34
	v_rcp_f32_e32 v35, v34
	v_mov_b32_e32 v34, v41
	v_pk_mul_f32 v[34:35], v[52:53], v[34:35]
	s_nop 0
	v_mul_f32_e32 v37, v34, v35
	v_cvt_pk_bf16_f32 v34, v46, v47
	v_cvt_pk_bf16_f32 v35, v44, v45
	v_cvt_pk_bf16_f32 v36, v48, v42
	v_cvt_pk_bf16_f32 v37, v40, v37
	flat_store_dwordx4 v[38:39], v[34:37]
	v_mov_b32_e32 v38, v30
	s_nop 0
	v_fmamk_f32 v36, v154, 0x3a000000, v223
	v_cmp_gt_f32_e32 vcc, s29, v36
	v_mul_f32_e32 v37, 0x4b800000, v36
; __device__ __forceinline__ unsigned pk2(float lo, float hi) { unsigned r; asm volatile("v_cvt_pk_bf16_f32 %0, %1, %2" : "=v"(r) : "v"(lo), "v"(hi)); return r; }
; #define PG8_BAR __builtin_amdgcn_s_barrier()
; template <class Epi, class Sched, bool ALIGN_EPI = false, bool SP2 = false>
; __device__ __forceinline__ void gemm_phase(PG8_LAS unsigned char* lds, const Gemm g, const Sched& S, const Epi& E) {
;     ...
;         if constexpr (ALIGN_EPI) { if (wr == 0) PG8_BAR; }
;         if (cur.ks == -2) E.mid(acc, cur, wr, wc, fr, fq); else E(acc, cur, wr, wc, fr, fq);
;         S.done(cur);
;         if (!has_next) break;
;         if (cur.ks != -2) {
; #pragma unroll
;         for (int a = 0; a < 2; ++a)
; #pragma unroll
;             for (int b = 0; b < 2; ++b)
; #pragma unroll
;                 for (int m = 0; m < 4; ++m)
; #pragma unroll
;                     for (int n = 0; n < 2; ++n) acc[a][b][m][n] = (f32x4){0.f, 0.f, 0.f, 0.f};
;         }
;         cur = nxt; cA = nA; cB = nB; ++ui;
;         if constexpr (ALIGN_EPI) { if (wr == 1) PG8_BAR; }
;     __device__ __forceinline__ void operator()(const f32x4 (&acc)[2][2][4][2], const Unit& u, int wr, int wc, int fr, int fq) const {
;     ...
;         for (int ai = 0; ai < 2; ++ai)
; #pragma unroll
;             for (int m = 0; m < 4; ++m) { bf16_t* rowp = O + (size_t)(row0 + ai * HALF + m * 16) * DFF + col0; const float rsv = rsqrtf(rs[ai][m] * (1.f / D) + EPS);
;                 const float rs2 = rsv * rsv, nrs = -1.4426950409f * rsv;
;                 float v[8];
; #pragma unroll
;                 for (int n = 0; n < 2; ++n)
; #pragma unroll
;                     for (int j = 0; j < 4; ++j) {
;                         const float g0 = acc[ai][0][m][n][j], u0 = acc[ai][1][m][n][j];
;                         v[n * 4 + j] = (g0 * u0) * (rs2 * __builtin_amdgcn_rcpf(1.0f + __builtin_amdgcn_exp2f(g0 * nrs))); }
;                 u32x4 w; w.x = pk2(v[0], v[1]); w.y = pk2(v[2], v[3]); w.z = pk2(v[4], v[5]); w.w = pk2(v[6], v[7]);
;                 *(u32x4*)rowp = w; }
	v_mad_i64_i32 v[34:35], s[2:3], v155, s34, v[140:141]
	v_cndmask_b32_e32 v36, v36, v37, vcc
	v_rsq_f32_e32 v36, v36
	s_nop 0
	v_mul_f32_e32 v37, 0x45800000, v36
	v_cndmask_b32_e32 v36, v36, v37, vcc
	v_mul_f32_e32 v40, 0xbfb8aa3b, v36
	v_mul_f32_e32 v37, v36, v36
	v_mul_f32_e32 v36, v30, v40
	v_exp_f32_e32 v36, v36
	s_nop 0
	v_add_f32_e32 v36, 1.0, v36
	v_rcp_f32_e32 v39, v36
	v_mov_b32_e32 v36, v26
	v_mul_f32_e32 v26, v31, v40
	v_exp_f32_e32 v26, v26
	v_pk_mul_f32 v[38:39], v[36:37], v[38:39]
	v_mov_b32_e32 v36, v27
	v_mul_f32_e32 v30, v38, v39
	v_add_f32_e32 v26, 1.0, v26
	v_rcp_f32_e32 v39, v26
	v_mov_b32_e32 v38, v31
	v_pk_mul_f32 v[26:27], v[36:37], v[38:39]
	s_nop 0
	v_mul_f32_e32 v31, v26, v27
	v_mul_f32_e32 v26, v32, v40
	v_exp_f32_e32 v26, v26
	v_mov_b32_e32 v36, v28
	v_add_f32_e32 v26, 1.0, v26
	v_rcp_f32_e32 v27, v26
	v_mov_b32_e32 v26, v32
	v_pk_mul_f32 v[26:27], v[36:37], v[26:27]
	s_nop 0
	v_mul_f32_e32 v28, v26, v27
	v_mul_f32_e32 v26, v33, v40
	v_exp_f32_e32 v26, v26
	v_mov_b32_e32 v36, v29
	v_add_f32_e32 v26, 1.0, v26
	v_rcp_f32_e32 v27, v26
	v_mov_b32_e32 v26, v33
	v_pk_mul_f32 v[26:27], v[36:37], v[26:27]
	s_nop 0
	v_mul_f32_e32 v29, v26, v27
	v_mul_f32_e32 v26, v22, v40
	v_exp_f32_e32 v26, v26
	v_mov_b32_e32 v36, v18
	v_mul_f32_e32 v18, v23, v40
	v_exp_f32_e32 v18, v18
	v_add_f32_e32 v26, 1.0, v26
	v_rcp_f32_e32 v27, v26
	v_mov_b32_e32 v26, v22
	v_add_f32_e32 v18, 1.0, v18
	v_pk_mul_f32 v[26:27], v[36:37], v[26:27]
	s_nop 0
	v_mul_f32_e32 v32, v26, v27
	v_rcp_f32_e32 v27, v18
	v_mov_b32_e32 v36, v19
	v_mov_b32_e32 v26, v23
	v_lshl_add_u64 v[22:23], v[34:35], 0, v[114:115]
	v_pk_mul_f32 v[18:19], v[36:37], v[26:27]
	v_mov_b32_e32 v36, v20
	v_mul_f32_e32 v26, v18, v19
	v_mul_f32_e32 v18, v24, v40
	v_exp_f32_e32 v18, v18
	s_nop 0
	v_add_f32_e32 v18, 1.0, v18
	v_rcp_f32_e32 v19, v18
	v_mov_b32_e32 v18, v24
	v_pk_mul_f32 v[18:19], v[36:37], v[18:19]
	s_nop 0
	v_mul_f32_e32 v24, v18, v19
	v_mul_f32_e32 v18, v25, v40
	v_exp_f32_e32 v18, v18
	v_mov_b32_e32 v36, v21
	v_add_f32_e32 v18, 1.0, v18
	v_rcp_f32_e32 v19, v18
	v_mov_b32_e32 v18, v25
	v_pk_mul_f32 v[18:19], v[36:37], v[18:19]
	s_nop 0
	v_mul_f32_e32 v21, v18, v19
	v_cvt_pk_bf16_f32 v18, v30, v31
	v_cvt_pk_bf16_f32 v19, v28, v29
	v_cvt_pk_bf16_f32 v20, v32, v26
	v_cvt_pk_bf16_f32 v21, v24, v21
	flat_store_dwordx4 v[22:23], v[18:21]
	v_mov_b32_e32 v22, v14
	s_nop 0
	v_fmamk_f32 v20, v152, 0x3a000000, v223
	v_cmp_gt_f32_e32 vcc, s29, v20
	v_mul_f32_e32 v21, 0x4b800000, v20
	v_mad_i64_i32 v[18:19], s[2:3], v153, s34, v[140:141]
	v_cndmask_b32_e32 v20, v20, v21, vcc
	v_rsq_f32_e32 v20, v20
	s_nop 0
	v_mul_f32_e32 v21, 0x45800000, v20
	v_cndmask_b32_e32 v20, v20, v21, vcc
	v_mul_f32_e32 v24, 0xbfb8aa3b, v20
	v_mul_f32_e32 v21, v20, v20
	v_mul_f32_e32 v20, v14, v24
	v_exp_f32_e32 v20, v20
	s_andn2_b64 vcc, exec, s[40:41]
	v_add_f32_e32 v20, 1.0, v20
	v_rcp_f32_e32 v23, v20
	v_mov_b32_e32 v20, v10
	v_mul_f32_e32 v10, v15, v24
	v_exp_f32_e32 v10, v10
	v_pk_mul_f32 v[22:23], v[20:21], v[22:23]
	v_mov_b32_e32 v20, v11
	v_mul_f32_e32 v14, v22, v23
	v_add_f32_e32 v10, 1.0, v10
	v_rcp_f32_e32 v23, v10
	v_mov_b32_e32 v22, v15
	v_pk_mul_f32 v[10:11], v[20:21], v[22:23]
	s_nop 0
	v_mul_f32_e32 v15, v10, v11
	v_mul_f32_e32 v10, v16, v24
	v_exp_f32_e32 v10, v10
	v_mov_b32_e32 v20, v12
	v_add_f32_e32 v10, 1.0, v10
	v_rcp_f32_e32 v11, v10
	v_mov_b32_e32 v10, v16
	v_pk_mul_f32 v[10:11], v[20:21], v[10:11]
	s_nop 0
	v_mul_f32_e32 v12, v10, v11
	v_mul_f32_e32 v10, v17, v24
	v_exp_f32_e32 v10, v10
	v_mov_b32_e32 v20, v13
	v_add_f32_e32 v10, 1.0, v10
	v_rcp_f32_e32 v11, v10
	v_mov_b32_e32 v10, v17
	v_pk_mul_f32 v[10:11], v[20:21], v[10:11]
	s_nop 0
	v_mul_f32_e32 v13, v10, v11
	v_mul_f32_e32 v10, v6, v24
	v_exp_f32_e32 v10, v10
	v_mov_b32_e32 v20, v2
	v_mul_f32_e32 v2, v7, v24
	v_exp_f32_e32 v2, v2
	v_add_f32_e32 v10, 1.0, v10
	v_rcp_f32_e32 v11, v10
	v_mov_b32_e32 v10, v6
	v_add_f32_e32 v2, 1.0, v2
	v_pk_mul_f32 v[10:11], v[20:21], v[10:11]
	s_nop 0
	v_mul_f32_e32 v16, v10, v11
	v_rcp_f32_e32 v11, v2
	v_mov_b32_e32 v20, v3
	v_mov_b32_e32 v10, v7
	v_lshl_add_u64 v[6:7], v[18:19], 0, v[114:115]
	v_pk_mul_f32 v[2:3], v[20:21], v[10:11]
	v_mov_b32_e32 v20, v4
	v_mul_f32_e32 v10, v2, v3
	v_mul_f32_e32 v2, v8, v24
	v_exp_f32_e32 v2, v2
	s_nop 0
	v_add_f32_e32 v2, 1.0, v2
	v_rcp_f32_e32 v3, v2
	v_mov_b32_e32 v2, v8
	v_pk_mul_f32 v[2:3], v[20:21], v[2:3]
	s_nop 0
	v_mul_f32_e32 v8, v2, v3
	v_mul_f32_e32 v2, v9, v24
	v_exp_f32_e32 v2, v2
	v_mov_b32_e32 v20, v5
	v_add_f32_e32 v2, 1.0, v2
	v_rcp_f32_e32 v3, v2
	v_mov_b32_e32 v2, v9
	v_pk_mul_f32 v[2:3], v[20:21], v[2:3]
	s_nop 0
	v_mul_f32_e32 v5, v2, v3
	v_cvt_pk_bf16_f32 v2, v14, v15
	v_cvt_pk_bf16_f32 v3, v12, v13
	v_cvt_pk_bf16_f32 v4, v16, v10
	v_cvt_pk_bf16_f32 v5, v8, v5
	flat_store_dwordx4 v[6:7], v[2:5]
	s_cbranch_vccnz .LBB0_1483
	s_andn2_b64 vcc, exec, s[14:15]
	s_cbranch_vccnz .LBB0_1482
	s_barrier
	s_branch .LBB0_1482
	s_nop 0
	s_nop 0
	s_nop 0
	s_nop 0
	s_nop 0
	s_nop 0
	s_nop 0
	s_nop 0
	s_nop 0
	s_nop 0
	s_nop 0
	s_nop 0
	s_nop 0
	s_nop 0
	s_nop 0
	s_nop 0
	s_nop 0
	s_nop 0
	s_nop 0
	s_nop 0
	s_nop 0
	s_nop 0
	s_nop 0
	s_nop 0
	s_nop 0
